# v118 + stick-breaking key loop: all 78 v_pk_add_f32 split into scalar v_add_f32 pairs (7.5)
# speedup vs baseline: 1.0048x; 1.0012x over previous
.LBB0_589:
	s_add_i32 s72, s65, 0xc0
	s_cmp_gt_i32 s72, s68
	s_cselect_b64 s[72:73], -1, 0
	s_or_b64 s[72:73], s[42:43], s[72:73]
	s_and_b64 vcc, exec, s[72:73]
	s_cbranch_vccnz .LBB0_594
	s_mul_i32 s42, s71, 0x8c00
	v_add_u32_e32 v188, s42, v157
	ds_read_b128 v[66:69], v188
	ds_read_b128 v[160:163], v188 offset:32
	ds_read_b128 v[82:85], v188 offset:8704
	ds_read_b128 v[164:167], v188 offset:8736
	v_add_u32_e32 v199, s65, v159
	v_add_u32_e32 v189, 0xe0, v199
	s_waitcnt lgkmcnt(1)
	v_mfma_f32_32x32x16_bf16 v[82:97], v[82:85], v[98:101], 0
	v_add_u32_e32 v190, 0xe1, v199
	v_cmp_lt_i32_e32 vcc, v189, v150
	v_add_u32_e32 v191, 0xe2, v199
	v_add_u32_e32 v192, 0xe3, v199
	v_add_u32_e32 v193, 0xe8, v199
	v_add_u32_e32 v204, 0xe9, v199
	v_add_u32_e32 v205, 0xea, v199
	s_waitcnt lgkmcnt(0)
	v_mfma_f32_32x32x16_bf16 v[82:97], v[164:167], v[102:105], v[82:97]
	ds_read_b128 v[164:167], v188 offset:8768
	ds_read_b128 v[168:171], v188 offset:8800
	v_add_u32_e32 v206, 0xeb, v199
	s_waitcnt lgkmcnt(1)
	v_mfma_f32_32x32x16_bf16 v[82:97], v[164:167], v[106:109], v[82:97]
	s_waitcnt lgkmcnt(0)
	v_mfma_f32_32x32x16_bf16 v[82:97], v[168:171], v[110:113], v[82:97]
	ds_read_b128 v[164:167], v188 offset:8832
	ds_read_b128 v[168:171], v188 offset:8864
	s_waitcnt lgkmcnt(1)
	v_mfma_f32_32x32x16_bf16 v[82:97], v[164:167], v[114:117], v[82:97]
	ds_read_b128 v[164:167], v188 offset:8896
	s_waitcnt lgkmcnt(1)
	v_mfma_f32_32x32x16_bf16 v[82:97], v[168:171], v[118:121], v[82:97]
	ds_read_b128 v[168:171], v188 offset:64
	ds_read_b128 v[172:175], v188 offset:96
	ds_read_b128 v[176:179], v188 offset:8928
	s_waitcnt lgkmcnt(3)
	v_mfma_f32_32x32x16_bf16 v[82:97], v[164:167], v[122:125], v[82:97]
	ds_read_b128 v[164:167], v188 offset:128
	ds_read_b128 v[180:183], v188 offset:160
	ds_read_b128 v[184:187], v188 offset:192
	ds_read_b128 v[200:203], v188 offset:224
	v_mfma_f32_32x32x16_bf16 v[66:81], v[66:69], v[98:101], 0
	s_waitcnt lgkmcnt(4)
	v_mfma_f32_32x32x16_bf16 v[82:97], v[176:179], v[126:129], v[82:97]
	v_mfma_f32_32x32x16_bf16 v[66:81], v[160:163], v[102:105], v[66:81]
	s_nop 10
	v_cndmask_b32_e32 v82, v194, v82, vcc
	v_cmp_lt_i32_e32 vcc, v190, v150
	v_exp_f32_e64 v176, -|v82|
	s_nop 0
	v_cndmask_b32_e32 v83, v194, v83, vcc
	v_cmp_lt_i32_e32 vcc, v191, v150
	v_exp_f32_e64 v177, -|v83|
	v_mfma_f32_32x32x16_bf16 v[66:81], v[168:171], v[106:109], v[66:81]
	v_cndmask_b32_e32 v84, v194, v84, vcc
	v_cmp_lt_i32_e32 vcc, v192, v150
	v_exp_f32_e64 v178, -|v84|
	v_add_f32_e64 v160, v176, 1.0
	v_add_f32_e64 v161, v177, 1.0
	v_cndmask_b32_e32 v85, v194, v85, vcc
	v_cmp_lt_i32_e32 vcc, v193, v150
	v_exp_f32_e64 v179, -|v85|
	v_log_f32_e32 v160, v160
	v_cndmask_b32_e32 v86, v194, v86, vcc
	v_cmp_lt_i32_e32 vcc, v204, v150
	v_exp_f32_e64 v188, -|v86|
	v_add_f32_e64 v176, v178, 1.0
	v_add_f32_e64 v177, v179, 1.0
	v_cndmask_b32_e32 v87, v194, v87, vcc
	v_exp_f32_e64 v189, -|v87|
	v_cmp_lt_i32_e32 vcc, v205, v150
	v_log_f32_e32 v161, v161
	v_log_f32_e32 v176, v176
	v_cndmask_b32_e32 v88, v194, v88, vcc
	v_cmp_lt_i32_e32 vcc, v206, v150
	v_add_f32_e64 v178, v188, 1.0
	v_add_f32_e64 v179, v189, 1.0
	v_exp_f32_e64 v190, -|v88|
	v_cndmask_b32_e32 v89, v194, v89, vcc
	v_exp_f32_e64 v191, -|v89|
	v_log_f32_e32 v177, v177
	v_log_f32_e32 v178, v178
	v_log_f32_e32 v179, v179
	v_max_f32_e32 v192, 0, v82
	v_max_f32_e32 v193, 0, v83
	v_max_f32_e32 v204, 0, v84
	v_max_f32_e32 v205, 0, v85
	v_max_f32_e32 v162, 0, v86
	v_max_f32_e32 v163, 0, v87
	v_mfma_f32_32x32x16_bf16 v[66:81], v[172:175], v[110:113], v[66:81]
	v_add_f32_e64 v188, v192, v160
	v_add_f32_e64 v189, v193, v161
	v_add_f32_e64 v160, v204, v176
	v_add_f32_e64 v161, v205, v177
	v_add_f32_e64 v176, v162, v178
	v_add_f32_e64 v177, v163, v179
	v_add_f32_e64 v162, v190, 1.0
	v_add_f32_e64 v163, v191, 1.0
	v_log_f32_e32 v168, v162
	v_max_f32_e32 v170, 0, v88
	v_add_u32_e32 v162, 0xf0, v199
	v_cmp_lt_i32_e32 vcc, v162, v150
	v_log_f32_e32 v169, v163
	s_waitcnt lgkmcnt(3)
	v_mfma_f32_32x32x16_bf16 v[66:81], v[164:167], v[114:117], v[66:81]
	v_cndmask_b32_e32 v162, v194, v90, vcc
	v_add_u32_e32 v90, 0xf1, v199
	v_cmp_lt_i32_e32 vcc, v90, v150
	v_exp_f32_e64 v90, -|v162|
	v_add_u32_e32 v167, 0xf2, v199
	v_cndmask_b32_e32 v163, v194, v91, vcc
	v_exp_f32_e64 v91, -|v163|
	v_max_f32_e32 v171, 0, v89
	v_cmp_lt_i32_e32 vcc, v167, v150
	v_add_f32_e64 v164, v170, v168
	v_add_f32_e64 v165, v171, v169
	v_add_f32_e64 v90, v90, 1.0
	v_add_f32_e64 v91, v91, 1.0
	v_cndmask_b32_e32 v168, v194, v92, vcc
	v_add_u32_e32 v92, 0xf3, v199
	v_cmp_lt_i32_e32 vcc, v92, v150
	v_log_f32_e32 v90, v90
	v_log_f32_e32 v91, v91
	v_cndmask_b32_e32 v169, v194, v93, vcc
	v_exp_f32_e64 v92, -|v168|
	v_exp_f32_e64 v93, -|v169|
	v_max_f32_e32 v166, 0, v162
	v_max_f32_e32 v167, 0, v163
	v_add_f32_e64 v170, v166, v90
	v_add_f32_e64 v171, v167, v91
	v_add_f32_e64 v90, v92, 1.0
	v_add_f32_e64 v91, v93, 1.0
	v_log_f32_e32 v92, v90
	v_max_f32_e32 v166, 0, v168
	v_add_u32_e32 v90, 0xf8, v199
	v_log_f32_e32 v93, v91
	v_cmp_lt_i32_e32 vcc, v90, v150
	v_add_u32_e32 v91, 0xf9, v199
	v_max_f32_e32 v167, 0, v169
	v_cndmask_b32_e32 v90, v194, v94, vcc
	v_cmp_lt_i32_e32 vcc, v91, v150
	v_exp_f32_e64 v94, -|v90|
	v_add_f32_e64 v174, v166, v92
	v_add_f32_e64 v175, v167, v93
	v_cndmask_b32_e32 v91, v194, v95, vcc
	v_exp_f32_e64 v95, -|v91|
	s_waitcnt lgkmcnt(2)
	v_mfma_f32_32x32x16_bf16 v[66:81], v[180:183], v[118:121], v[66:81]
	v_max_f32_e32 v167, 0, v91
	v_add_f32_e64 v92, v94, 1.0
	v_add_f32_e64 v93, v95, 1.0
	v_mov_b32_e32 v180, v174
	v_log_f32_e32 v94, v92
	v_max_f32_e32 v166, 0, v90
	v_add_u32_e32 v92, 0xfa, v199
	v_log_f32_e32 v95, v93
	v_cmp_lt_i32_e32 vcc, v92, v150
	v_add_u32_e32 v93, 0xfb, v199
	v_mov_b32_e32 v181, v170
	v_cndmask_b32_e32 v92, v194, v96, vcc
	v_cmp_lt_i32_e32 vcc, v93, v150
	v_exp_f32_e64 v96, -|v92|
	v_add_f32_e64 v172, v166, v94
	v_add_f32_e64 v173, v167, v95
	v_cndmask_b32_e32 v93, v194, v97, vcc
	v_exp_f32_e64 v97, -|v93|
	v_mov_b32_e32 v170, v175
	v_add_f32_e64 v182, v180, v170
	v_add_f32_e64 v183, v181, v171
	v_mov_b32_e32 v170, v171
	v_add_f32_e64 v94, v96, 1.0
	v_add_f32_e64 v95, v97, 1.0
	v_log_f32_e32 v94, v94
	v_log_f32_e32 v95, v95
	v_max_f32_e32 v96, 0, v92
	v_max_f32_e32 v97, 0, v93
	v_add_f32_e64 v94, v96, v94
	v_add_f32_e64 v95, v97, v95
	v_mov_b32_e32 v96, v160
	v_mov_b32_e32 v171, v183
	v_and_b32_e32 v160, 64, v195
	v_add_f32_e64 v180, v170, v182
	v_add_f32_e64 v181, v171, v182
	v_mov_b32_e32 v170, v94
	v_mov_b32_e32 v171, v172
	v_mov_b32_e32 v172, v95
	v_xor_b32_e32 v94, 32, v195
	v_add_u32_e32 v160, 64, v160
	s_waitcnt lgkmcnt(1)
	v_mfma_f32_32x32x16_bf16 v[66:81], v[184:187], v[122:125], v[66:81]
	v_add_f32_e64 v170, v170, v172
	v_add_f32_e64 v171, v171, v173
	v_cmp_lt_i32_e32 vcc, v94, v160
	v_mov_b32_e32 v178, v164
	v_mov_b32_e32 v179, v176
	v_mov_b32_e32 v176, v165
	v_mov_b32_e32 v172, v173
	v_mov_b32_e32 v173, v171
	v_cndmask_b32_e32 v94, v195, v94, vcc
	v_mov_b32_e32 v97, v188
	v_mov_b32_e32 v188, v161
	v_add_f32_e64 v178, v178, v176
	v_add_f32_e64 v179, v179, v177
	v_add_f32_e64 v172, v172, v170
	v_add_f32_e64 v173, v173, v170
	v_lshlrev_b32_e32 v164, 2, v94
	v_add_f32_e64 v166, v96, v188
	v_add_f32_e64 v167, v97, v189
	v_mov_b32_e32 v96, v189
	v_mov_b32_e32 v176, v177
	v_mov_b32_e32 v177, v179
	ds_bpermute_b32 v189, v164, v181
	ds_bpermute_b32 v188, v164, v173
	v_mov_b32_e32 v97, v167
	v_add_f32_e64 v176, v176, v178
	v_add_f32_e64 v177, v177, v178
	v_add_f32_e64 v96, v96, v166
	v_add_f32_e64 v97, v97, v166
	ds_bpermute_b32 v160, v164, v177
	ds_bpermute_b32 v192, v164, v97
	v_mov_b32_e32 v184, v173
	v_mov_b32_e32 v185, v181
	s_waitcnt lgkmcnt(2)
	v_add_f32_e64 v190, v184, v188
	v_add_f32_e64 v191, v185, v189
	v_mfma_f32_32x32x16_bf16 v[66:81], v[200:203], v[126:129], v[66:81]
	v_add_f32_e64 v186, v190, v191
	v_add_f32_e64 v187, v191, v190
	s_waitcnt lgkmcnt(1)
	v_add_f32_e32 v185, v177, v160
	v_mov_b32_e32 v184, v97
	v_mov_b32_e32 v193, v186
	s_waitcnt lgkmcnt(0)
	v_add_f32_e64 v184, v184, v192
	v_add_f32_e64 v185, v185, v193
	s_nop 0
	v_add_f32_e32 v94, v184, v185
	v_add_f32_e32 v94, v0, v94
	v_cmp_le_f32_e32 vcc, s49, v94
	s_cmp_eq_u64 vcc, exec
	s_cbranch_scc1 .LBB0_592
	v_add_u32_e32 v167, 0xc0, v199
	v_cmp_lt_i32_e32 vcc, v167, v150
	v_add_u32_e32 v167, 0xc1, v199
	v_add_f32_e32 v179, 0, v94
	v_cndmask_b32_e32 v66, v194, v66, vcc
	v_cmp_lt_i32_e32 vcc, v167, v150
	v_exp_f32_e64 v200, -|v66|
	v_max_f32_e32 v167, v66, v66
	v_cndmask_b32_e32 v67, v194, v67, vcc
	v_exp_f32_e64 v201, -|v67|
	v_max_f32_e32 v202, 0, v167
	v_add_u32_e32 v167, 0xc2, v199
	v_cmp_lt_i32_e32 vcc, v167, v150
	v_add_u32_e32 v167, 0xc3, v199
	v_add_f32_e64 v200, v200, 1.0
	v_add_f32_e64 v201, v201, 1.0
	v_cndmask_b32_e32 v68, v194, v68, vcc
	v_cmp_lt_i32_e32 vcc, v167, v150
	v_log_f32_e32 v200, v200
	v_log_f32_e32 v201, v201
	v_cndmask_b32_e32 v69, v194, v69, vcc
	v_exp_f32_e64 v204, -|v68|
	v_exp_f32_e64 v205, -|v69|
	v_max_f32_e32 v203, 0, v67
	v_add_f32_e64 v200, v202, v200
	v_add_f32_e64 v201, v203, v201
	v_add_f32_e64 v202, v204, 1.0
	v_add_f32_e64 v203, v205, 1.0
	v_max_f32_e32 v204, 0, v68
	v_add_u32_e32 v167, 0xc8, v199
	v_cmp_lt_i32_e32 vcc, v167, v150
	v_add_u32_e32 v167, 0xc9, v199
	v_log_f32_e32 v202, v202
	v_cndmask_b32_e32 v70, v194, v70, vcc
	v_cmp_lt_i32_e32 vcc, v167, v150
	v_log_f32_e32 v203, v203
	v_exp_f32_e64 v206, -|v70|
	v_cndmask_b32_e32 v71, v194, v71, vcc
	v_exp_f32_e64 v207, -|v71|
	v_max_f32_e32 v205, 0, v69
	v_add_f32_e64 v202, v204, v202
	v_add_f32_e64 v203, v205, v203
	v_add_f32_e64 v204, v206, 1.0
	v_add_f32_e64 v205, v207, 1.0
	v_max_f32_e32 v206, 0, v70
	v_add_u32_e32 v167, 0xca, v199
	v_cmp_lt_i32_e32 vcc, v167, v150
	v_add_u32_e32 v167, 0xcb, v199
	v_log_f32_e32 v204, v204
	v_cndmask_b32_e32 v72, v194, v72, vcc
	v_cmp_lt_i32_e32 vcc, v167, v150
	v_log_f32_e32 v205, v205
	v_exp_f32_e64 v208, -|v72|
	v_cndmask_b32_e32 v73, v194, v73, vcc
	v_exp_f32_e64 v209, -|v73|
	v_max_f32_e32 v207, 0, v71
	v_add_f32_e64 v204, v206, v204
	v_add_f32_e64 v205, v207, v205
	v_add_f32_e64 v206, v208, 1.0
	v_add_f32_e64 v207, v209, 1.0
	v_max_f32_e32 v208, 0, v72
	v_add_u32_e32 v167, 0xd0, v199
	v_cmp_lt_i32_e32 vcc, v167, v150
	v_add_u32_e32 v167, 0xd1, v199
	v_log_f32_e32 v206, v206
	v_cndmask_b32_e32 v74, v194, v74, vcc
	v_cmp_lt_i32_e32 vcc, v167, v150
	v_log_f32_e32 v207, v207
	v_exp_f32_e64 v210, -|v74|
	v_cndmask_b32_e32 v75, v194, v75, vcc
	v_exp_f32_e64 v211, -|v75|
	v_max_f32_e32 v209, 0, v73
	v_add_f32_e64 v206, v208, v206
	v_add_f32_e64 v207, v209, v207
	v_add_f32_e64 v208, v210, 1.0
	v_add_f32_e64 v209, v211, 1.0
	v_max_f32_e32 v210, 0, v74
	v_add_u32_e32 v167, 0xd2, v199
	v_cmp_lt_i32_e32 vcc, v167, v150
	v_add_u32_e32 v167, 0xd3, v199
	v_log_f32_e32 v208, v208
	v_cndmask_b32_e32 v76, v194, v76, vcc
	v_cmp_lt_i32_e32 vcc, v167, v150
	v_log_f32_e32 v209, v209
	v_exp_f32_e64 v212, -|v76|
	v_cndmask_b32_e32 v77, v194, v77, vcc
	v_exp_f32_e64 v213, -|v77|
	v_max_f32_e32 v211, 0, v75
	v_add_f32_e64 v208, v210, v208
	v_add_f32_e64 v209, v211, v209
	v_add_f32_e64 v210, v212, 1.0
	v_add_f32_e64 v211, v213, 1.0
	v_max_f32_e32 v212, 0, v76
	v_add_u32_e32 v167, 0xd8, v199
	v_cmp_lt_i32_e32 vcc, v167, v150
	v_add_u32_e32 v167, 0xd9, v199
	v_log_f32_e32 v210, v210
	v_cndmask_b32_e32 v78, v194, v78, vcc
	v_cmp_lt_i32_e32 vcc, v167, v150
	v_log_f32_e32 v211, v211
	v_exp_f32_e64 v214, -|v78|
	v_cndmask_b32_e32 v79, v194, v79, vcc
	v_exp_f32_e64 v215, -|v79|
	v_max_f32_e32 v213, 0, v77
	v_add_f32_e64 v210, v212, v210
	v_add_f32_e64 v211, v213, v211
	v_add_f32_e64 v212, v214, 1.0
	v_add_f32_e64 v213, v215, 1.0
	v_max_f32_e32 v214, 0, v78
	v_add_u32_e32 v167, 0xda, v199
	v_cmp_lt_i32_e32 vcc, v167, v150
	v_add_u32_e32 v167, 0xdb, v199
	v_log_f32_e32 v212, v212
	v_cndmask_b32_e32 v80, v194, v80, vcc
	v_cmp_lt_i32_e32 vcc, v167, v150
	v_log_f32_e32 v213, v213
	v_exp_f32_e64 v216, -|v80|
	v_cndmask_b32_e32 v81, v194, v81, vcc
	v_exp_f32_e64 v217, -|v81|
	v_max_f32_e32 v215, 0, v79
	v_add_f32_e64 v212, v214, v212
	v_add_f32_e64 v213, v215, v213
	v_add_f32_e64 v214, v216, 1.0
	v_add_f32_e64 v215, v217, 1.0
	v_log_f32_e32 v214, v214
	v_log_f32_e32 v215, v215
	v_max_f32_e32 v216, 0, v80
	v_max_f32_e32 v217, 0, v81
	v_add_f32_e64 v214, v216, v214
	v_add_f32_e64 v215, v217, v215
	v_mov_b32_e32 v220, v210
	v_mov_b32_e32 v221, v208
	v_mov_b32_e32 v208, v211
	v_mov_b32_e32 v222, v214
	v_mov_b32_e32 v223, v212
	v_mov_b32_e32 v212, v215
	v_add_f32_e64 v220, v220, v208
	v_add_f32_e64 v221, v221, v209
	v_add_f32_e64 v222, v222, v212
	v_add_f32_e64 v223, v223, v213
	v_mov_b32_e32 v208, v209
	v_mov_b32_e32 v209, v221
	v_mov_b32_e32 v212, v213
	v_mov_b32_e32 v213, v223
	v_add_f32_e64 v208, v208, v220
	v_add_f32_e64 v209, v209, v220
	v_add_f32_e64 v212, v212, v222
	v_add_f32_e64 v213, v213, v222
	ds_bpermute_b32 v226, v164, v209
	ds_bpermute_b32 v227, v164, v213
	v_mov_b32_e32 v216, v202
	v_mov_b32_e32 v217, v200
	v_mov_b32_e32 v200, v203
	v_mov_b32_e32 v218, v206
	v_mov_b32_e32 v219, v204
	v_mov_b32_e32 v204, v207
	v_add_f32_e64 v216, v216, v200
	v_add_f32_e64 v217, v217, v201
	v_add_f32_e64 v218, v218, v204
	v_add_f32_e64 v219, v219, v205
	v_mov_b32_e32 v200, v201
	v_mov_b32_e32 v201, v217
	v_mov_b32_e32 v204, v205
	v_mov_b32_e32 v205, v219
	v_mov_b32_e32 v221, v211
	v_mov_b32_e32 v210, v209
	v_mov_b32_e32 v211, v213
	v_add_f32_e64 v200, v200, v216
	v_add_f32_e64 v201, v201, v216
	v_add_f32_e64 v204, v204, v218
	v_add_f32_e64 v205, v205, v218
	s_waitcnt lgkmcnt(0)
	v_add_f32_e64 v210, v210, v226
	v_add_f32_e64 v211, v211, v227
	ds_bpermute_b32 v202, v164, v201
	ds_bpermute_b32 v167, v164, v205
	v_cndmask_b32_e64 v164, 0, v226, s[4:5]
	v_add_f32_e32 v184, v94, v211
	v_add_f32_e32 v164, v164, v184
	v_add_f32_e64 v220, v220, v164
	v_add_f32_e64 v221, v221, v164
	s_waitcnt lgkmcnt(0)
	v_cndmask_b32_e64 v174, 0, v167, s[4:5]
	v_add_f32_e64 v76, v76, -v220
	v_add_f32_e64 v77, v77, -v221
	v_mov_b32_e32 v219, v207
	v_exp_f32_e32 v184, v77
	v_exp_f32_e32 v187, v76
	v_add_f32_e64 v76, v209, v164
	v_add_f32_e64 v77, v208, v164
	v_add_f32_e64 v74, v74, -v76
	v_add_f32_e64 v75, v75, -v77
	v_mov_b32_e32 v217, v203
	v_exp_f32_e32 v77, v75
	v_exp_f32_e32 v164, v74
	v_add_f32_e64 v74, v210, v211
	v_add_f32_e64 v75, v211, v210
	v_cndmask_b32_e64 v171, 0, v202, s[4:5]
	v_add_f32_e32 v75, v94, v74
	v_add_f32_e32 v76, v174, v75
	v_add_f32_e64 v206, v218, v76
	v_add_f32_e64 v207, v219, v76
	v_mov_b32_e32 v203, v74
	v_add_f32_e64 v72, v72, -v206
	v_add_f32_e64 v73, v73, -v207
	v_cndmask_b32_e64 v183, 0, v227, s[4:5]
	v_exp_f32_e32 v174, v73
	v_exp_f32_e32 v191, v72
	v_add_f32_e64 v72, v205, v76
	v_add_f32_e64 v73, v204, v76
	v_add_f32_e64 v70, v70, -v72
	v_add_f32_e64 v71, v71, -v73
	v_mov_b32_e32 v223, v215
	v_exp_f32_e32 v73, v71
	v_exp_f32_e32 v76, v70
	v_add_f32_e32 v71, v205, v167
	v_mov_b32_e32 v70, v201
	v_add_f32_e64 v70, v70, v202
	v_add_f32_e64 v71, v71, v203
	s_nop 0
	v_add_f32_e32 v72, v94, v71
	v_add_f32_e32 v72, v171, v72
	v_add_f32_e64 v74, v216, v72
	v_add_f32_e64 v75, v217, v72
	s_nop 0
	v_add_f32_e64 v68, v68, -v74
	v_add_f32_e64 v69, v69, -v75
	s_nop 0
	v_exp_f32_e32 v74, v69
	v_exp_f32_e32 v75, v68
	v_add_f32_e64 v68, v201, v72
	v_add_f32_e64 v69, v200, v72
	v_add_f32_e64 v66, v66, -v68
	v_add_f32_e64 v67, v67, -v69
	s_nop 0
	v_exp_f32_e32 v167, v66
	v_add_f32_e32 v66, v179, v183
	v_exp_f32_e32 v72, v67
	v_add_f32_e64 v68, v213, v66
	v_add_f32_e64 v69, v212, v66
	v_add_f32_e64 v67, v223, v66
	v_add_f32_e64 v66, v222, v66
	v_add_f32_e64 v68, v78, -v68
	v_add_f32_e64 v69, v79, -v69
	v_add_f32_e64 v66, v80, -v66
	v_add_f32_e64 v67, v81, -v67
	v_exp_f32_e32 v68, v68
	v_exp_f32_e32 v69, v69
	v_exp_f32_e32 v78, v66
	v_exp_f32_e32 v79, v67
	v_add_f32_e32 v66, v70, v71
	v_add_f32_e32 v94, v94, v66
	v_cvt_pk_bf16_f32 v70, v167, v72
	v_cvt_pk_bf16_f32 v71, v75, v74
	v_cvt_pk_bf16_f32 v72, v76, v73
	v_cvt_pk_bf16_f32 v73, v191, v174
	v_cvt_pk_bf16_f32 v66, v164, v77
	v_cvt_pk_bf16_f32 v67, v187, v184
	v_cvt_pk_bf16_f32 v68, v68, v69
	v_cvt_pk_bf16_f32 v69, v78, v79
	s_branch .LBB0_593

.LBB0_593:
	v_cndmask_b32_e64 v74, 0, v189, s[4:5]
	v_add_f32_e32 v75, v0, v190
	v_mov_b32_e32 v183, v175
	v_add_f32_e32 v74, v74, v75
	v_add_f32_e64 v76, v182, v74
	v_add_f32_e64 v77, v183, v74
	v_add_f32_e64 v75, v180, v74
	v_add_f32_e64 v74, v181, v74
	v_add_f32_e64 v74, v162, -v74
	v_add_f32_e64 v75, v163, -v75
	v_cndmask_b32_e64 v79, 0, v160, s[4:5]
	v_exp_f32_e32 v163, v74
	v_add_f32_e32 v74, v0, v186
	v_add_f32_e64 v76, v168, -v76
	v_add_f32_e64 v77, v169, -v77
	v_add_f32_e32 v74, v79, v74
	v_mov_b32_e32 v179, v165
	v_exp_f32_e32 v168, v77
	v_exp_f32_e32 v169, v76
	v_exp_f32_e32 v162, v75
	v_add_f32_e64 v76, v178, v74
	v_add_f32_e64 v77, v179, v74
	v_add_f32_e64 v75, v176, v74
	v_add_f32_e64 v74, v177, v74
	v_add_f32_e64 v76, v88, -v76
	v_add_f32_e64 v77, v89, -v77
	v_add_f32_e64 v74, v86, -v74
	v_add_f32_e64 v75, v87, -v75
	v_mov_b32_e32 v167, v161
	v_add_u32_e32 v161, s42, v198
	v_exp_f32_e32 v88, v77
	v_exp_f32_e32 v89, v76
	v_exp_f32_e32 v165, v75
	v_exp_f32_e32 v174, v74
	ds_read_b128 v[74:77], v161 offset:17408
	v_cndmask_b32_e64 v78, 0, v192, s[4:5]
	v_add_f32_e32 v160, 0, v0
	v_add_f32_e32 v0, v0, v185
	v_add_f32_e32 v0, v78, v0
	v_add_f32_e64 v78, v166, v0
	v_add_f32_e64 v79, v167, v0
	v_cndmask_b32_e64 v164, 0, v188, s[4:5]
	v_add_f32_e64 v78, v84, -v78
	v_add_f32_e64 v79, v85, -v79
	v_mov_b32_e32 v171, v95
	v_exp_f32_e32 v84, v79
	v_exp_f32_e32 v85, v78
	v_add_f32_e64 v78, v97, v0
	v_add_f32_e64 v79, v96, v0
	v_add_f32_e64 v82, v82, -v78
	v_add_f32_e64 v83, v83, -v79
	ds_read_b128 v[78:81], v161 offset:17440
	s_waitcnt lgkmcnt(1)
	v_mfma_f32_32x32x16_bf16 v[50:65], v[74:77], v[70:73], v[50:65]
	v_add_f32_e32 v0, v160, v164
	v_add_f32_e64 v74, v0, v173
	v_add_f32_e64 v75, v0, v172
	v_exp_f32_e32 v96, v83
	v_exp_f32_e32 v97, v82
	v_add_f32_e64 v82, v90, -v74
	v_add_f32_e64 v83, v91, -v75
	ds_read_b128 v[74:77], v161 offset:17472
	v_exp_f32_e32 v90, v82
	s_waitcnt lgkmcnt(1)
	v_mfma_f32_32x32x16_bf16 v[50:65], v[78:81], v[66:69], v[50:65]
	v_exp_f32_e32 v91, v83
	v_cvt_pk_bf16_f32 v78, v97, v96
	v_cvt_pk_bf16_f32 v79, v85, v84
	v_cvt_pk_bf16_f32 v80, v174, v165
	v_cvt_pk_bf16_f32 v81, v89, v88
	ds_read_b128 v[82:85], v161 offset:17504
	v_add_f32_e64 v86, v0, v170
	v_add_f32_e64 v87, v0, v171
	s_waitcnt lgkmcnt(1)
	v_mfma_f32_32x32x16_bf16 v[50:65], v[74:77], v[78:81], v[50:65]
	v_add_f32_e64 v74, v92, -v86
	v_add_f32_e64 v75, v93, -v87
	v_cvt_pk_bf16_f32 v76, v90, v91
	v_exp_f32_e32 v0, v74
	v_exp_f32_e32 v77, v75
	v_cvt_pk_bf16_f32 v74, v163, v162
	v_cvt_pk_bf16_f32 v75, v169, v168
	v_cmp_le_f32_e32 vcc, s49, v94
	v_cvt_pk_bf16_f32 v77, v0, v77
	s_cmp_eq_u64 vcc, exec
	s_cselect_b64 s[42:43], -1, 0
	s_waitcnt lgkmcnt(0)
	v_mfma_f32_32x32x16_bf16 v[50:65], v[82:85], v[74:77], v[50:65]
	ds_read_b128 v[82:85], v161 offset:22016
	ds_read_b128 v[86:89], v161 offset:22048
	v_mov_b32_e32 v0, v94
	s_waitcnt lgkmcnt(1)
	v_mfma_f32_32x32x16_bf16 v[34:49], v[82:85], v[70:73], v[34:49]
	s_waitcnt lgkmcnt(0)
	v_mfma_f32_32x32x16_bf16 v[34:49], v[86:89], v[66:69], v[34:49]
	ds_read_b128 v[82:85], v161 offset:22080
	ds_read_b128 v[86:89], v161 offset:22112
	s_waitcnt lgkmcnt(1)
	v_mfma_f32_32x32x16_bf16 v[34:49], v[82:85], v[78:81], v[34:49]
	s_waitcnt lgkmcnt(0)
	v_mfma_f32_32x32x16_bf16 v[34:49], v[86:89], v[74:77], v[34:49]
	ds_read_b128 v[82:85], v161 offset:26624
	ds_read_b128 v[86:89], v161 offset:26656
	s_waitcnt lgkmcnt(1)
	v_mfma_f32_32x32x16_bf16 v[18:33], v[82:85], v[70:73], v[18:33]
	s_waitcnt lgkmcnt(0)
	v_mfma_f32_32x32x16_bf16 v[18:33], v[86:89], v[66:69], v[18:33]
	ds_read_b128 v[82:85], v161 offset:26688
	ds_read_b128 v[86:89], v161 offset:26720
	s_waitcnt lgkmcnt(1)
	v_mfma_f32_32x32x16_bf16 v[18:33], v[82:85], v[78:81], v[18:33]
	s_waitcnt lgkmcnt(0)
	v_mfma_f32_32x32x16_bf16 v[18:33], v[86:89], v[74:77], v[18:33]
	ds_read_b128 v[82:85], v161 offset:31232
	ds_read_b128 v[86:89], v161 offset:31264
	s_waitcnt lgkmcnt(1)
	v_mfma_f32_32x32x16_bf16 v[2:17], v[82:85], v[70:73], v[2:17]
	s_waitcnt lgkmcnt(0)
	v_mfma_f32_32x32x16_bf16 v[2:17], v[86:89], v[66:69], v[2:17]
	ds_read_b128 v[66:69], v161 offset:31296
	ds_read_b128 v[70:73], v161 offset:31328
	s_waitcnt lgkmcnt(1)
	v_mfma_f32_32x32x16_bf16 v[2:17], v[66:69], v[78:81], v[2:17]
	s_waitcnt lgkmcnt(0)
	v_mfma_f32_32x32x16_bf16 v[2:17], v[70:73], v[74:77], v[2:17]
